# static s_setprio 1 for the wave-slot-odd co-resident workgroup (one priority raise at entry)
# baseline (speedup 1.0000x reference)
; __global__ void __launch_bounds__(256, 2) mega(Params p) {
;   extern __shared__ __attribute__((aligned(16))) unsigned char lds[];
;   const int tid = threadIdx.x;
;   volatile unsigned* bst = (volatile unsigned*)(lds + 73728 + 16);
;   XcdBarrier xb{};
;   if (tid == 0) { bst[0] = 0u; bst[1] = 0u; bst[2] = 0u; bst[3] = 0u; }
_Z4mega6Params:
	s_getreg_b32 s8, hwreg(HW_REG_HW_ID, 0, 4)
	s_bitcmp1_b32 s8, 0
	s_cbranch_scc0 .Lprio_skip
	s_setprio 1
.Lprio_skip:
	s_load_dwordx2 s[88:89], s[0:1], 0x80
	s_load_dwordx4 s[4:7], s[0:1], 0x88
	s_mov_b32 s26, s2
	v_and_b32_e32 v180, 0x3ff, v0
	s_mov_b32 s8, 0
	s_waitcnt lgkmcnt(0)
	v_writelane_b32 v247, s4, 0
	s_nop 1
	v_writelane_b32 v247, s5, 1
	v_writelane_b32 v247, s6, 2
	v_writelane_b32 v247, s7, 3
	v_cmp_eq_u32_e64 s[4:5], 0, v180
	s_mov_b64 s[2:3], exec
	s_nop 0
	v_writelane_b32 v247, s4, 4
	s_nop 1
	v_writelane_b32 v247, s5, 5
	s_and_b64 s[4:5], s[2:3], s[4:5]
	s_mov_b64 exec, s[4:5]
	s_cbranch_execz .LBB0_2
	s_mov_b64 s[4:5], src_shared_base
	s_add_i32 s4, 0, 0x12010
	s_cmp_lg_u32 s4, -1
	s_cselect_b32 s4, s4, 0
	s_cselect_b32 s6, s5, 0
	v_mov_b32_e32 v2, s4
	s_add_i32 s4, 0, 0x12014
	s_cmp_lg_u32 s4, -1
	v_mov_b32_e32 v3, s6
	v_mov_b32_e32 v1, 0
	s_cselect_b32 s4, s4, 0
	flat_store_dword v[2:3], v1 sc0 sc1
	s_waitcnt vmcnt(0)
	s_cselect_b32 s6, s5, 0
	v_mov_b32_e32 v2, s4
	s_add_i32 s4, 0, 0x12018
	s_cmp_lg_u32 s4, -1
	v_mov_b32_e32 v3, s6
	s_cselect_b32 s4, s4, 0
	flat_store_dword v[2:3], v1 sc0 sc1
	s_waitcnt vmcnt(0)
	s_cselect_b32 s6, s5, 0
	v_mov_b32_e32 v2, s4
	s_add_i32 s4, 0, 0x1201c
	s_cmp_lg_u32 s4, -1
	v_mov_b32_e32 v3, s6
	s_cselect_b32 s4, s4, 0
	s_cselect_b32 s5, s5, 0
	flat_store_dword v[2:3], v1 sc0 sc1
	s_waitcnt vmcnt(0)
	v_mov_b32_e32 v2, s4
	v_mov_b32_e32 v3, s5
	flat_store_dword v[2:3], v1 sc0 sc1
	s_waitcnt vmcnt(0)
